# down-GEMM residual epilogue rewritten by hand: all x loads 5 row-groups ahead via saddr global loads, counted vmcnt, global stores
# speedup vs baseline: 1.0248x; 1.0110x over previous
;     __device__ __forceinline__ void load_x(f32x4 (&x)[2][2], size_t off) const {
; #pragma unroll
;         for (int bj = 0; bj < 2; ++bj) {
;             if constexpr (XIN_F32) { x[bj][0] = *(const f32x4*)((const float*)xin + off + bj * HALF); x[bj][1] = *(const f32x4*)((const float*)xin + off + bj * HALF + 4); }
;             else { const u32x4 w = *(const u32x4*)((const bf16_t*)xin + off + bj * HALF);
;                 x[bj][0] = (f32x4){__builtin_bit_cast(float, w.x << 16), __builtin_bit_cast(float, w.x & 0xffff0000u), __builtin_bit_cast(float, w.y << 16), __builtin_bit_cast(float, w.y & 0xffff0000u)};
;                 x[bj][1] = (f32x4){__builtin_bit_cast(float, w.z << 16), __builtin_bit_cast(float, w.z & 0xffff0000u), __builtin_bit_cast(float, w.w << 16), __builtin_bit_cast(float, w.w & 0xffff0000u)}; } }
;     }
;     __device__ __forceinline__ void operator()(const f32x4 (&acc)[2][2][4][2], const Unit& u, int wr, int wc, int fr, int fq) const {
;         const int row0 = u.pm * BM + wr * 64 + fr; const int col0 = u.pn * BM + wc * 32 + 8 * fq;
;         const int b = (u.pm * BM) >> 12;
;         f32x4 gv[2][2];
; #pragma unroll
;         for (int bj = 0; bj < 2; ++bj)
; #pragma unroll
;             for (int n = 0; n < 2; ++n) gv[bj][n] = *(const f32x4*)(gate + (size_t)b * gate_ld + col0 + bj * HALF + n * 4);
;         f32x4 xv[2][2][2];
;         load_x(xv[0], (size_t)row0 * 1024 + col0);
; #pragma unroll
;         for (int g = 0; g < 8; ++g) { const int ai = g >> 2, m = g & 3; const size_t off = (size_t)(row0 + ai * HALF + m * 16) * 1024 + col0;
;             if (g + 1 < 8) { const int ai2 = (g + 1) >> 2, m2 = (g + 1) & 3; load_x(xv[(g + 1) & 1], (size_t)(row0 + ai2 * HALF + m2 * 16) * 1024 + col0); }
;             float rs_ = 1.0f; if constexpr (ROWSCALE) rs_ = tab[((u.pm == pm0 ? 0 : 256) + ai * HALF + wr * 64 + m * 16 + fr) * 2 + 1];
; #pragma unroll
;             for (int bj = 0; bj < 2; ++bj) { const f32x4 v0 = xv[g & 1][bj][0] + gv[bj][0] * (acc[ai][bj][m][0] * rs_), v1 = xv[g & 1][bj][1] + gv[bj][1] * (acc[ai][bj][m][1] * rs_);
;                 u32x4 w; w.x = cvt_pk_bf16(v0[0], v0[1]); w.y = cvt_pk_bf16(v0[2], v0[3]); w.z = cvt_pk_bf16(v1[0], v1[1]); w.w = cvt_pk_bf16(v1[2], v1[3]);
;                 *(u32x4*)(out + off + bj * HALF) = w; } }
.LBB0_708:
	s_ashr_i32 s3, s65, 4
	s_mul_hi_i32 s5, s3, 0x6000
	s_mulk_i32 s3, 0x6000
	s_add_u32 s4, s57, s3
	s_addc_u32 s5, s58, s5
	v_lshl_or_b32 v213, s66, 8, v194
	v_lshlrev_b32_e32 v220, 2, v213
	global_load_dwordx4 v[60:63], v220, s[4:5]
	global_load_dwordx4 v[56:59], v220, s[4:5] offset:16
	global_load_dwordx4 v[52:55], v220, s[4:5] offset:512
	global_load_dwordx4 v[48:51], v220, s[4:5] offset:528
	v_lshlrev_b32_e32 v212, 11, v192
	v_lshl_add_u32 v212, v213, 1, v212
	s_lshl_b32 s3, s65, 19
	s_add_u32 s98, s40, s3
	s_addc_u32 s99, s41, 0
	s_mov_b64 s[100:101], s[98:99]
	global_load_dwordx4 v[156:159], v212, s[98:99]
	global_load_dwordx4 v[176:179], v212, s[98:99] offset:256
	s_add_u32 s98, s98, 0x8000
	s_addc_u32 s99, s99, 0
	global_load_dwordx4 v[180:183], v212, s[98:99]
	global_load_dwordx4 v[184:187], v212, s[98:99] offset:256
	s_add_u32 s98, s98, 0x8000
	s_addc_u32 s99, s99, 0
	global_load_dwordx4 v[188:191], v212, s[98:99]
	global_load_dwordx4 v[196:199], v212, s[98:99] offset:256
	s_add_u32 s98, s98, 0x8000
	s_addc_u32 s99, s99, 0
	global_load_dwordx4 v[200:203], v212, s[98:99]
	global_load_dwordx4 v[224:227], v212, s[98:99] offset:256
	s_add_u32 s98, s98, 0x28000
	s_addc_u32 s99, s99, 0
	global_load_dwordx4 v[228:231], v212, s[98:99]
	global_load_dwordx4 v[232:235], v212, s[98:99] offset:256
	s_add_u32 s98, s98, 0x8000
	s_addc_u32 s99, s99, 0
	s_waitcnt vmcnt(8)
	v_lshlrev_b32_e32 v160, 16, v156
	v_and_b32_e32 v161, 0xffff0000, v156
	v_lshlrev_b32_e32 v174, 16, v157
	v_and_b32_e32 v175, 0xffff0000, v157
	v_lshlrev_b32_e32 v204, 16, v158
	v_and_b32_e32 v205, 0xffff0000, v158
	v_lshlrev_b32_e32 v210, 16, v159
	v_and_b32_e32 v211, 0xffff0000, v159
	v_pk_fma_f32 v[142:143], v[142:143], v[60:61], v[160:161]
	v_pk_fma_f32 v[144:145], v[144:145], v[62:63], v[174:175]
	v_pk_fma_f32 v[138:139], v[138:139], v[56:57], v[204:205]
	v_pk_fma_f32 v[140:141], v[140:141], v[58:59], v[210:211]
	v_cvt_pk_bf16_f32 v156, v142, v143
	v_cvt_pk_bf16_f32 v157, v144, v145
	v_cvt_pk_bf16_f32 v158, v138, v139
	v_cvt_pk_bf16_f32 v159, v140, v141
	global_store_dwordx4 v212, v[156:159], s[100:101]
	v_lshlrev_b32_e32 v160, 16, v176
	v_and_b32_e32 v161, 0xffff0000, v176
	v_lshlrev_b32_e32 v174, 16, v177
	v_and_b32_e32 v175, 0xffff0000, v177
	v_lshlrev_b32_e32 v204, 16, v178
	v_and_b32_e32 v205, 0xffff0000, v178
	v_lshlrev_b32_e32 v210, 16, v179
	v_and_b32_e32 v211, 0xffff0000, v179
	v_pk_fma_f32 v[134:135], v[134:135], v[52:53], v[160:161]
	v_pk_fma_f32 v[136:137], v[136:137], v[54:55], v[174:175]
	v_pk_fma_f32 v[130:131], v[130:131], v[48:49], v[204:205]
	v_pk_fma_f32 v[132:133], v[132:133], v[50:51], v[210:211]
	v_cvt_pk_bf16_f32 v176, v134, v135
	v_cvt_pk_bf16_f32 v177, v136, v137
	v_cvt_pk_bf16_f32 v178, v130, v131
	v_cvt_pk_bf16_f32 v179, v132, v133
	global_store_dwordx4 v212, v[176:179], s[100:101] offset:256
	s_add_u32 s100, s100, 0x8000
	s_addc_u32 s101, s101, 0
	global_load_dwordx4 v[156:159], v212, s[98:99]
	global_load_dwordx4 v[176:179], v212, s[98:99] offset:256
	s_add_u32 s98, s98, 0x8000
	s_addc_u32 s99, s99, 0
	s_waitcnt vmcnt(10)
	v_lshlrev_b32_e32 v160, 16, v180
	v_and_b32_e32 v161, 0xffff0000, v180
	v_lshlrev_b32_e32 v174, 16, v181
	v_and_b32_e32 v175, 0xffff0000, v181
	v_lshlrev_b32_e32 v204, 16, v182
	v_and_b32_e32 v205, 0xffff0000, v182
	v_lshlrev_b32_e32 v210, 16, v183
	v_and_b32_e32 v211, 0xffff0000, v183
	v_pk_fma_f32 v[126:127], v[126:127], v[60:61], v[160:161]
	v_pk_fma_f32 v[128:129], v[128:129], v[62:63], v[174:175]
	v_pk_fma_f32 v[122:123], v[122:123], v[56:57], v[204:205]
	v_pk_fma_f32 v[124:125], v[124:125], v[58:59], v[210:211]
	v_cvt_pk_bf16_f32 v180, v126, v127
	v_cvt_pk_bf16_f32 v181, v128, v129
	v_cvt_pk_bf16_f32 v182, v122, v123
	v_cvt_pk_bf16_f32 v183, v124, v125
	global_store_dwordx4 v212, v[180:183], s[100:101]
	v_lshlrev_b32_e32 v160, 16, v184
	v_and_b32_e32 v161, 0xffff0000, v184
	v_lshlrev_b32_e32 v174, 16, v185
	v_and_b32_e32 v175, 0xffff0000, v185
	v_lshlrev_b32_e32 v204, 16, v186
	v_and_b32_e32 v205, 0xffff0000, v186
	v_lshlrev_b32_e32 v210, 16, v187
	v_and_b32_e32 v211, 0xffff0000, v187
	v_pk_fma_f32 v[118:119], v[118:119], v[52:53], v[160:161]
	v_pk_fma_f32 v[120:121], v[120:121], v[54:55], v[174:175]
	v_pk_fma_f32 v[114:115], v[114:115], v[48:49], v[204:205]
	v_pk_fma_f32 v[116:117], v[116:117], v[50:51], v[210:211]
	v_cvt_pk_bf16_f32 v184, v118, v119
	v_cvt_pk_bf16_f32 v185, v120, v121
	v_cvt_pk_bf16_f32 v186, v114, v115
	v_cvt_pk_bf16_f32 v187, v116, v117
	global_store_dwordx4 v212, v[184:187], s[100:101] offset:256
	s_add_u32 s100, s100, 0x8000
	s_addc_u32 s101, s101, 0
	global_load_dwordx4 v[180:183], v212, s[98:99]
	global_load_dwordx4 v[184:187], v212, s[98:99] offset:256
	s_add_u32 s98, s98, 0x8000
	s_addc_u32 s99, s99, 0
	s_waitcnt vmcnt(12)
	v_lshlrev_b32_e32 v160, 16, v188
	v_and_b32_e32 v161, 0xffff0000, v188
	v_lshlrev_b32_e32 v174, 16, v189
	v_and_b32_e32 v175, 0xffff0000, v189
	v_lshlrev_b32_e32 v204, 16, v190
	v_and_b32_e32 v205, 0xffff0000, v190
	v_lshlrev_b32_e32 v210, 16, v191
	v_and_b32_e32 v211, 0xffff0000, v191
	v_pk_fma_f32 v[110:111], v[110:111], v[60:61], v[160:161]
	v_pk_fma_f32 v[112:113], v[112:113], v[62:63], v[174:175]
	v_pk_fma_f32 v[106:107], v[106:107], v[56:57], v[204:205]
	v_pk_fma_f32 v[108:109], v[108:109], v[58:59], v[210:211]
	v_cvt_pk_bf16_f32 v188, v110, v111
	v_cvt_pk_bf16_f32 v189, v112, v113
	v_cvt_pk_bf16_f32 v190, v106, v107
	v_cvt_pk_bf16_f32 v191, v108, v109
	global_store_dwordx4 v212, v[188:191], s[100:101]
	v_lshlrev_b32_e32 v160, 16, v196
	v_and_b32_e32 v161, 0xffff0000, v196
	v_lshlrev_b32_e32 v174, 16, v197
	v_and_b32_e32 v175, 0xffff0000, v197
	v_lshlrev_b32_e32 v204, 16, v198
	v_and_b32_e32 v205, 0xffff0000, v198
	v_lshlrev_b32_e32 v210, 16, v199
	v_and_b32_e32 v211, 0xffff0000, v199
	v_pk_fma_f32 v[102:103], v[102:103], v[52:53], v[160:161]
	v_pk_fma_f32 v[104:105], v[104:105], v[54:55], v[174:175]
	v_pk_fma_f32 v[98:99], v[98:99], v[48:49], v[204:205]
	v_pk_fma_f32 v[100:101], v[100:101], v[50:51], v[210:211]
	v_cvt_pk_bf16_f32 v196, v102, v103
	v_cvt_pk_bf16_f32 v197, v104, v105
	v_cvt_pk_bf16_f32 v198, v98, v99
	v_cvt_pk_bf16_f32 v199, v100, v101
	global_store_dwordx4 v212, v[196:199], s[100:101] offset:256
	s_add_u32 s100, s100, 0x8000
	s_addc_u32 s101, s101, 0
	global_load_dwordx4 v[188:191], v212, s[98:99]
	global_load_dwordx4 v[196:199], v212, s[98:99] offset:256
	s_add_u32 s98, s98, 0x8000
	s_addc_u32 s99, s99, 0
	s_waitcnt vmcnt(14)
; __device__ __forceinline__ unsigned cvt_pk_bf16(float lo, float hi) { f32x2_cv v = {lo, hi}; bf16x2_cv b = __builtin_convertvector(v, bf16x2_cv); return __builtin_bit_cast(unsigned, b); }
;     __device__ __forceinline__ void operator()(const f32x4 (&acc)[2][2][4][2], const Unit& u, int wr, int wc, int fr, int fq) const {
;     ...
;         for (int g = 0; g < 8; ++g) { const int ai = g >> 2, m = g & 3; const size_t off = (size_t)(row0 + ai * HALF + m * 16) * 1024 + col0;
;             if (g + 1 < 8) { const int ai2 = (g + 1) >> 2, m2 = (g + 1) & 3; load_x(xv[(g + 1) & 1], (size_t)(row0 + ai2 * HALF + m2 * 16) * 1024 + col0); }
;             float rs_ = 1.0f; if constexpr (ROWSCALE) rs_ = tab[((u.pm == pm0 ? 0 : 256) + ai * HALF + wr * 64 + m * 16 + fr) * 2 + 1];
; #pragma unroll
;             for (int bj = 0; bj < 2; ++bj) { const f32x4 v0 = xv[g & 1][bj][0] + gv[bj][0] * (acc[ai][bj][m][0] * rs_), v1 = xv[g & 1][bj][1] + gv[bj][1] * (acc[ai][bj][m][1] * rs_);
;                 u32x4 w; w.x = cvt_pk_bf16(v0[0], v0[1]); w.y = cvt_pk_bf16(v0[2], v0[3]); w.z = cvt_pk_bf16(v1[0], v1[1]); w.w = cvt_pk_bf16(v1[2], v1[3]);
;                 *(u32x4*)(out + off + bj * HALF) = w; } }
	v_lshlrev_b32_e32 v160, 16, v200
	v_and_b32_e32 v161, 0xffff0000, v200
	v_lshlrev_b32_e32 v174, 16, v201
	v_and_b32_e32 v175, 0xffff0000, v201
	v_lshlrev_b32_e32 v204, 16, v202
	v_and_b32_e32 v205, 0xffff0000, v202
	v_lshlrev_b32_e32 v210, 16, v203
	v_and_b32_e32 v211, 0xffff0000, v203
	v_pk_fma_f32 v[94:95], v[94:95], v[60:61], v[160:161]
	v_pk_fma_f32 v[96:97], v[96:97], v[62:63], v[174:175]
	v_pk_fma_f32 v[90:91], v[90:91], v[56:57], v[204:205]
	v_pk_fma_f32 v[92:93], v[92:93], v[58:59], v[210:211]
	v_cvt_pk_bf16_f32 v200, v94, v95
	v_cvt_pk_bf16_f32 v201, v96, v97
	v_cvt_pk_bf16_f32 v202, v90, v91
	v_cvt_pk_bf16_f32 v203, v92, v93
	global_store_dwordx4 v212, v[200:203], s[100:101]
	v_lshlrev_b32_e32 v160, 16, v224
	v_and_b32_e32 v161, 0xffff0000, v224
	v_lshlrev_b32_e32 v174, 16, v225
	v_and_b32_e32 v175, 0xffff0000, v225
	v_lshlrev_b32_e32 v204, 16, v226
	v_and_b32_e32 v205, 0xffff0000, v226
	v_lshlrev_b32_e32 v210, 16, v227
	v_and_b32_e32 v211, 0xffff0000, v227
	v_pk_fma_f32 v[86:87], v[86:87], v[52:53], v[160:161]
	v_pk_fma_f32 v[88:89], v[88:89], v[54:55], v[174:175]
	v_pk_fma_f32 v[82:83], v[82:83], v[48:49], v[204:205]
	v_pk_fma_f32 v[84:85], v[84:85], v[50:51], v[210:211]
	v_cvt_pk_bf16_f32 v224, v86, v87
	v_cvt_pk_bf16_f32 v225, v88, v89
	v_cvt_pk_bf16_f32 v226, v82, v83
	v_cvt_pk_bf16_f32 v227, v84, v85
	global_store_dwordx4 v212, v[224:227], s[100:101] offset:256
	s_add_u32 s100, s100, 0x28000
	s_addc_u32 s101, s101, 0
	s_waitcnt vmcnt(14)
	v_lshlrev_b32_e32 v160, 16, v228
	v_and_b32_e32 v161, 0xffff0000, v228
	v_lshlrev_b32_e32 v174, 16, v229
	v_and_b32_e32 v175, 0xffff0000, v229
	v_lshlrev_b32_e32 v204, 16, v230
	v_and_b32_e32 v205, 0xffff0000, v230
	v_lshlrev_b32_e32 v210, 16, v231
	v_and_b32_e32 v211, 0xffff0000, v231
	v_pk_fma_f32 v[76:77], v[76:77], v[60:61], v[160:161]
	v_pk_fma_f32 v[78:79], v[78:79], v[62:63], v[174:175]
	v_pk_fma_f32 v[72:73], v[72:73], v[56:57], v[204:205]
	v_pk_fma_f32 v[74:75], v[74:75], v[58:59], v[210:211]
	v_cvt_pk_bf16_f32 v228, v76, v77
	v_cvt_pk_bf16_f32 v229, v78, v79
	v_cvt_pk_bf16_f32 v230, v72, v73
	v_cvt_pk_bf16_f32 v231, v74, v75
	global_store_dwordx4 v212, v[228:231], s[100:101]
	v_lshlrev_b32_e32 v160, 16, v232
	v_and_b32_e32 v161, 0xffff0000, v232
	v_lshlrev_b32_e32 v174, 16, v233
	v_and_b32_e32 v175, 0xffff0000, v233
	v_lshlrev_b32_e32 v204, 16, v234
	v_and_b32_e32 v205, 0xffff0000, v234
	v_lshlrev_b32_e32 v210, 16, v235
	v_and_b32_e32 v211, 0xffff0000, v235
	v_pk_fma_f32 v[68:69], v[68:69], v[52:53], v[160:161]
	v_pk_fma_f32 v[70:71], v[70:71], v[54:55], v[174:175]
	v_pk_fma_f32 v[64:65], v[64:65], v[48:49], v[204:205]
	v_pk_fma_f32 v[66:67], v[66:67], v[50:51], v[210:211]
	v_cvt_pk_bf16_f32 v232, v68, v69
	v_cvt_pk_bf16_f32 v233, v70, v71
	v_cvt_pk_bf16_f32 v234, v64, v65
	v_cvt_pk_bf16_f32 v235, v66, v67
	global_store_dwordx4 v212, v[232:235], s[100:101] offset:256
	s_add_u32 s100, s100, 0x8000
	s_addc_u32 s101, s101, 0
	s_waitcnt vmcnt(12)
	v_lshlrev_b32_e32 v160, 16, v156
	v_and_b32_e32 v161, 0xffff0000, v156
	v_lshlrev_b32_e32 v174, 16, v157
	v_and_b32_e32 v175, 0xffff0000, v157
	v_lshlrev_b32_e32 v204, 16, v158
	v_and_b32_e32 v205, 0xffff0000, v158
	v_lshlrev_b32_e32 v210, 16, v159
	v_and_b32_e32 v211, 0xffff0000, v159
	v_pk_fma_f32 v[44:45], v[44:45], v[60:61], v[160:161]
	v_pk_fma_f32 v[46:47], v[46:47], v[62:63], v[174:175]
	v_pk_fma_f32 v[40:41], v[40:41], v[56:57], v[204:205]
	v_pk_fma_f32 v[42:43], v[42:43], v[58:59], v[210:211]
	v_cvt_pk_bf16_f32 v156, v44, v45
	v_cvt_pk_bf16_f32 v157, v46, v47
	v_cvt_pk_bf16_f32 v158, v40, v41
	v_cvt_pk_bf16_f32 v159, v42, v43
	global_store_dwordx4 v212, v[156:159], s[100:101]
	v_lshlrev_b32_e32 v160, 16, v176
	v_and_b32_e32 v161, 0xffff0000, v176
	v_lshlrev_b32_e32 v174, 16, v177
	v_and_b32_e32 v175, 0xffff0000, v177
	v_lshlrev_b32_e32 v204, 16, v178
	v_and_b32_e32 v205, 0xffff0000, v178
	v_lshlrev_b32_e32 v210, 16, v179
	v_and_b32_e32 v211, 0xffff0000, v179
	v_pk_fma_f32 v[36:37], v[36:37], v[52:53], v[160:161]
	v_pk_fma_f32 v[38:39], v[38:39], v[54:55], v[174:175]
	v_pk_fma_f32 v[32:33], v[32:33], v[48:49], v[204:205]
	v_pk_fma_f32 v[34:35], v[34:35], v[50:51], v[210:211]
	v_cvt_pk_bf16_f32 v176, v36, v37
	v_cvt_pk_bf16_f32 v177, v38, v39
	v_cvt_pk_bf16_f32 v178, v32, v33
	v_cvt_pk_bf16_f32 v179, v34, v35
	global_store_dwordx4 v212, v[176:179], s[100:101] offset:256
	s_add_u32 s100, s100, 0x8000
	s_addc_u32 s101, s101, 0
	s_waitcnt vmcnt(10)
; __device__ __forceinline__ unsigned cvt_pk_bf16(float lo, float hi) { f32x2_cv v = {lo, hi}; bf16x2_cv b = __builtin_convertvector(v, bf16x2_cv); return __builtin_bit_cast(unsigned, b); }
;     __device__ __forceinline__ void operator()(const f32x4 (&acc)[2][2][4][2], const Unit& u, int wr, int wc, int fr, int fq) const {
;     ...
;         for (int g = 0; g < 8; ++g) { const int ai = g >> 2, m = g & 3; const size_t off = (size_t)(row0 + ai * HALF + m * 16) * 1024 + col0;
;             if (g + 1 < 8) { const int ai2 = (g + 1) >> 2, m2 = (g + 1) & 3; load_x(xv[(g + 1) & 1], (size_t)(row0 + ai2 * HALF + m2 * 16) * 1024 + col0); }
;             float rs_ = 1.0f; if constexpr (ROWSCALE) rs_ = tab[((u.pm == pm0 ? 0 : 256) + ai * HALF + wr * 64 + m * 16 + fr) * 2 + 1];
; #pragma unroll
;             for (int bj = 0; bj < 2; ++bj) { const f32x4 v0 = xv[g & 1][bj][0] + gv[bj][0] * (acc[ai][bj][m][0] * rs_), v1 = xv[g & 1][bj][1] + gv[bj][1] * (acc[ai][bj][m][1] * rs_);
;                 u32x4 w; w.x = cvt_pk_bf16(v0[0], v0[1]); w.y = cvt_pk_bf16(v0[2], v0[3]); w.z = cvt_pk_bf16(v1[0], v1[1]); w.w = cvt_pk_bf16(v1[2], v1[3]);
;                 *(u32x4*)(out + off + bj * HALF) = w; } }
	v_lshlrev_b32_e32 v160, 16, v180
	v_and_b32_e32 v161, 0xffff0000, v180
	v_lshlrev_b32_e32 v174, 16, v181
	v_and_b32_e32 v175, 0xffff0000, v181
	v_lshlrev_b32_e32 v204, 16, v182
	v_and_b32_e32 v205, 0xffff0000, v182
	v_lshlrev_b32_e32 v210, 16, v183
	v_and_b32_e32 v211, 0xffff0000, v183
	v_pk_fma_f32 v[28:29], v[28:29], v[60:61], v[160:161]
	v_pk_fma_f32 v[30:31], v[30:31], v[62:63], v[174:175]
	v_pk_fma_f32 v[24:25], v[24:25], v[56:57], v[204:205]
	v_pk_fma_f32 v[26:27], v[26:27], v[58:59], v[210:211]
	v_cvt_pk_bf16_f32 v180, v28, v29
	v_cvt_pk_bf16_f32 v181, v30, v31
	v_cvt_pk_bf16_f32 v182, v24, v25
	v_cvt_pk_bf16_f32 v183, v26, v27
	global_store_dwordx4 v212, v[180:183], s[100:101]
	v_lshlrev_b32_e32 v160, 16, v184
	v_and_b32_e32 v161, 0xffff0000, v184
	v_lshlrev_b32_e32 v174, 16, v185
	v_and_b32_e32 v175, 0xffff0000, v185
	v_lshlrev_b32_e32 v204, 16, v186
	v_and_b32_e32 v205, 0xffff0000, v186
	v_lshlrev_b32_e32 v210, 16, v187
	v_and_b32_e32 v211, 0xffff0000, v187
	v_pk_fma_f32 v[20:21], v[20:21], v[52:53], v[160:161]
	v_pk_fma_f32 v[22:23], v[22:23], v[54:55], v[174:175]
	v_pk_fma_f32 v[16:17], v[16:17], v[48:49], v[204:205]
	v_pk_fma_f32 v[18:19], v[18:19], v[50:51], v[210:211]
	v_cvt_pk_bf16_f32 v184, v20, v21
	v_cvt_pk_bf16_f32 v185, v22, v23
	v_cvt_pk_bf16_f32 v186, v16, v17
	v_cvt_pk_bf16_f32 v187, v18, v19
	global_store_dwordx4 v212, v[184:187], s[100:101] offset:256
	s_add_u32 s100, s100, 0x8000
	s_addc_u32 s101, s101, 0
	s_waitcnt vmcnt(8)
	v_lshlrev_b32_e32 v160, 16, v188
	v_and_b32_e32 v161, 0xffff0000, v188
	v_lshlrev_b32_e32 v174, 16, v189
	v_and_b32_e32 v175, 0xffff0000, v189
	v_lshlrev_b32_e32 v204, 16, v190
	v_and_b32_e32 v205, 0xffff0000, v190
	v_lshlrev_b32_e32 v210, 16, v191
	v_and_b32_e32 v211, 0xffff0000, v191
	v_pk_fma_f32 v[12:13], v[12:13], v[60:61], v[160:161]
	v_pk_fma_f32 v[14:15], v[14:15], v[62:63], v[174:175]
	v_pk_fma_f32 v[8:9], v[8:9], v[56:57], v[204:205]
	v_pk_fma_f32 v[10:11], v[10:11], v[58:59], v[210:211]
	v_cvt_pk_bf16_f32 v188, v12, v13
	v_cvt_pk_bf16_f32 v189, v14, v15
	v_cvt_pk_bf16_f32 v190, v8, v9
	v_cvt_pk_bf16_f32 v191, v10, v11
	global_store_dwordx4 v212, v[188:191], s[100:101]
	v_lshlrev_b32_e32 v160, 16, v196
	v_and_b32_e32 v161, 0xffff0000, v196
	v_lshlrev_b32_e32 v174, 16, v197
	v_and_b32_e32 v175, 0xffff0000, v197
	v_lshlrev_b32_e32 v204, 16, v198
	v_and_b32_e32 v205, 0xffff0000, v198
	v_lshlrev_b32_e32 v210, 16, v199
	v_and_b32_e32 v211, 0xffff0000, v199
	v_pk_fma_f32 v[4:5], v[4:5], v[52:53], v[160:161]
	v_pk_fma_f32 v[6:7], v[6:7], v[54:55], v[174:175]
	v_pk_fma_f32 v[0:1], v[0:1], v[48:49], v[204:205]
	v_pk_fma_f32 v[2:3], v[2:3], v[50:51], v[210:211]
	v_cvt_pk_bf16_f32 v196, v4, v5
	v_cvt_pk_bf16_f32 v197, v6, v7
	v_cvt_pk_bf16_f32 v198, v0, v1
	v_cvt_pk_bf16_f32 v199, v2, v3
	global_store_dwordx4 v212, v[196:199], s[100:101] offset:256
	s_add_u32 s100, s100, 0x8000
	s_addc_u32 s101, s101, 0
	s_mov_b64 s[4:5], -1
	s_and_b64 vcc, exec, s[36:37]
	s_cbranch_vccnz .LBB0_693
	s_andn2_b64 vcc, exec, s[14:15]
	s_cbranch_vccnz .LBB0_692
	s_barrier
	s_branch .LBB0_692
